# v92 + phase-0: non-SSM workgroups start 2.8 us late (they have slack; the SSM workgroups' rms job runs uncontended)
# speedup vs baseline: 1.0134x; 1.0129x over previous
.LBB0_19:
	s_cmp_lt_i32 s26, 1
	s_cselect_b64 s[10:11], -1, 0
	s_cmp_gt_i32 s27, 0
	s_cselect_b64 s[0:1], -1, 0
	s_cmpk_lt_i32 s96, 0x440
	s_cselect_b64 s[4:5], -1, 0
	s_and_b64 s[4:5], s[4:5], s[10:11]
	s_and_b64 s[0:1], s[4:5], s[0:1]
	v_writelane_b32 v254, s96, 37
	s_mov_b32 s13, 0
	s_andn2_b64 vcc, exec, s[0:1]
	v_and_b32_e32 v228, 15, v0
	v_writelane_b32 v254, s26, 38
	s_nop 1
	v_writelane_b32 v254, s27, 39
	s_cbranch_vccnz .LBB0_103
	s_cmpk_lt_u32 s96, 0x80
	s_cbranch_scc1 .Lp0_lag
	s_sleep 100
.Lp0_lag:
	v_and_b32_e32 v1, 0x3ff, v0
	v_lshlrev_b32_e32 v8, 3, v1
	v_and_b32_e32 v4, 0xf8, v8
	v_mul_u32_u24_e32 v6, 0x41, v4
	v_bfe_u32 v89, v0, 5, 5
	v_lshlrev_b32_e32 v6, 2, v6
	s_add_u32 s0, s78, 0x600000
	v_lshlrev_b32_e32 v7, 2, v89
	v_add_u32_e32 v9, 0, v6
	s_addc_u32 s1, s79, 0
	v_add3_u32 v90, 0, v7, v6
	v_add_u32_e32 v91, v9, v7
	v_or_b32_e32 v7, 0x200, v1
	v_bfe_u32 v2, v0, 4, 6
	v_mov_b32_e32 v3, 0xffff9800
	s_add_u32 s92, s78, 0x580000
	v_lshrrev_b32_e32 v92, 5, v7
	v_and_or_b32 v86, v2, 28, v3
	v_lshlrev_b32_e32 v3, 2, v1
	s_addc_u32 s93, s79, 0
	s_movk_i32 s2, 0xf8
	v_lshlrev_b32_e32 v7, 2, v92
	v_and_b32_e32 v5, 0xfc, v3
	s_add_u32 s94, s78, 0x380000
	v_add3_u32 v93, 0, v7, v6
	v_add_u32_e32 v94, v9, v7
	v_or_b32_e32 v7, 0x600, v1
	v_bitop3_b32 v3, v3, s2, v3 bitop3:0xc
	s_addc_u32 s95, s79, 0
	v_lshrrev_b32_e32 v96, 5, v7
	v_add_u32_e32 v101, 0, v3
	v_lshlrev_b32_e32 v3, 6, v1
	v_readlane_b32 s16, v254, 5
	s_mov_b32 s90, s96
	s_add_u32 s96, s78, 0x180000
	v_lshlrev_b32_e32 v7, 2, v96
	v_and_b32_e32 v3, 64, v3
	v_lshlrev_b32_e32 v66, 2, v5
	v_mov_b32_e32 v67, 0
	v_readlane_b32 s17, v254, 6
	v_readlane_b32 s20, v254, 9
	v_readlane_b32 s21, v254, 10
	s_addc_u32 s97, s79, 0
	v_add_u32_e32 v98, v9, v7
	v_mul_u32_u24_e32 v9, 0x78, v1
	v_add_u32_e32 v102, 0, v3
	v_lshlrev_b32_e32 v3, 4, v1
	v_lshl_add_u64 v[68:69], s[16:17], 0, v[66:67]
	v_lshl_add_u64 v[70:71], s[20:21], 0, v[66:67]
	s_add_u32 s14, s78, 0x80000
	v_mul_u32_u24_e32 v11, 0x88, v1
	v_bfe_u32 v100, v1, 4, 2
	v_and_b32_e32 v66, 0x3f0, v3
	v_add3_u32 v3, v9, v8, 0
	s_movk_i32 s2, 0x4200
	s_addc_u32 s15, s79, 0
	v_add_u32_e32 v103, 0x200, v3
	v_add3_u32 v104, v3, v11, s2
	v_lshl_add_u32 v3, v100, 9, 0
	s_add_u32 s80, s78, 0x800000
	v_bfe_u32 v87, v0, 6, 4
	v_add_u32_e32 v107, 0x2200, v3
	v_lshl_add_u32 v3, v228, 3, 0
	s_addc_u32 s81, s79, 0
	v_add_u32_e32 v108, 0x200, v3
	v_lshl_add_u32 v3, v87, 3, 0
	s_add_u32 s34, s78, 0x1600000
	v_add_u32_e32 v109, 0x4200, v3
	v_mbcnt_lo_u32_b32 v3, -1, 0
	s_addc_u32 s35, s79, 0
	v_add_u32_e32 v99, 0, v8
	s_movk_i32 s4, 0x78
	v_mbcnt_hi_u32_b32 v110, -1, v3
	v_readlane_b32 s18, v254, 7
	v_readlane_b32 s19, v254, 8
	v_readlane_b32 s22, v254, 11
	v_readlane_b32 s23, v254, 12
	v_readlane_b32 s24, v254, 13
	v_readlane_b32 s25, v254, 14
	v_readlane_b32 s26, v254, 15
	v_readlane_b32 s27, v254, 16
	v_readlane_b32 s28, v254, 17
	v_readlane_b32 s29, v254, 18
	v_readlane_b32 s30, v254, 19
	v_readlane_b32 s31, v254, 20
	v_writelane_b32 v254, s0, 40
	v_and_b32_e32 v2, 63, v0
	v_add3_u32 v97, 0, v7, v6
	s_add_u32 s52, s78, 0xe800000
	v_mad_u32_u24 v10, v1, s4, v99
	v_lshl_add_u64 v[6:7], s[78:79], 0, v[66:67]
	s_mov_b64 s[4:5], 0x2a00000
	v_lshlrev_b32_e32 v66, 1, v5
	v_and_b32_e32 v3, 64, v110
	v_writelane_b32 v254, s1, 41
	v_lshl_add_u32 v88, v2, 2, 0
	v_or_b32_e32 v95, 32, v89
	s_addc_u32 s53, s79, 0
	v_cmp_gt_u32_e64 s[0:1], 64, v1
	v_lshl_add_u64 v[72:73], v[6:7], 0, s[4:5]
	v_lshl_add_u64 v[74:75], s[76:77], 0, v[66:67]
	v_add_u32_e32 v105, 0x2200, v99
	v_or_b32_e32 v106, 0xfffffe00, v1
	v_add_u32_e32 v111, 64, v3
	v_xor_b32_e32 v112, 32, v110
	v_xor_b32_e32 v113, 16, v110
	s_mov_b32 s54, 0x3a800000
	s_mov_b32 s2, 0x800000
	v_lshlrev_b32_e32 v76, 2, v2
	v_lshlrev_b32_e32 v78, 1, v4
	s_mov_b32 s91, 0x3fb8aa3b
	s_mov_b32 s82, 0xc2ce8ed0
	s_mov_b32 s55, 0x42b17218
	s_mov_b32 s83, 0xdb629599
	s_mov_b32 s84, 0xf534ddc0
	s_mov_b32 s85, 0xfc2757d1
	s_mov_b32 s86, 0x4e441529
	s_mov_b32 s87, 0xa2f9836e
	s_mov_b32 s88, 0x3fc90fda
	s_mov_b32 s89, 0xbfc90fda
	v_mov_b32_e32 v114, 0x3c0881c4
	v_mov_b32_e32 v115, 0xbab64f3b
	v_add_u32_e32 v116, v10, v11
	v_xor_b32_e32 v117, 8, v110
	v_mov_b32_e32 v118, 0x7f800000
	v_not_b32_e32 v119, 63
	v_not_b32_e32 v120, 31
	v_mov_b32_e32 v121, 0x7fc00000
	s_mov_b64 s[56:57], 0x800
	s_mov_b32 s98, s3
	s_movk_i32 s99, 0x440
	s_cmpk_lg_u32 s3, 0x100
	s_cbranch_scc1 .Lp0_bal_done
	s_mov_b32 s98, 0xfffffc40
	s_cmpk_lt_u32 s90, 0x80
	s_cbranch_scc0 .Lp0_others
	s_addk_i32 s90, 0x3c0
	s_branch .Lp0_bal_done
